# attention: V fragment reads 7 deep (private register ring v190-v205 + v212-v227), decision chain behind first PV MFMAs, K reads before DMA; P0a loads in flight; cg sync removed
# speedup vs baseline: 1.0130x; 1.0007x over previous
.LBB0_695:
	s_lshl_b32 s43, s34, 13
	s_mov_b32 s42, s38
	v_lshl_add_u32 v185, s42, 13, v184
	ds_read_b128 v[112:115], v185 offset:49152
	ds_read_b128 v[186:189], v185 offset:49664
	s_add_i32 s38, s43, s39
	s_mov_b32 m0, s38
	v_lshl_add_u64 v[212:213], s[68:69], 0, v[166:167]
	global_load_lds_dwordx4 v[172:173], off
	s_lshl_b32 s38, s34, 14
	s_add_i32 s45, s38, s24
	s_mov_b32 m0, s45
	v_lshl_add_u64 v[214:215], s[68:69], 0, v[170:171]
	global_load_lds_dwordx4 v[212:213], off
	s_add_i32 s38, s38, s25
	s_mov_b32 m0, s38
	s_mov_b32 s38, s44
	global_load_lds_dwordx4 v[214:215], off
	s_waitcnt lgkmcnt(1)
	v_mfma_f32_32x32x16_bf16 v[128:143], v[112:115], v[156:159], v[64:79]
	ds_read_b128 v[190:193], v185 offset:51200
	ds_read_b128 v[194:197], v185 offset:51712
	v_add_f32_e32 v116, 0, v96
	v_add_f32_e32 v117, 0, v97
	v_add_f32_e32 v116, v98, v116
	v_add_f32_e32 v117, v99, v117
	v_cvt_pk_bf16_f32 v96, v96, v97
	v_cvt_pk_bf16_f32 v97, v98, v99
	v_cvt_pk_bf16_f32 v98, v100, v101
	v_cvt_pk_bf16_f32 v99, v102, v103
	s_nop 0
	v_add_f32_e32 v100, v100, v116
	v_add_f32_e32 v101, v101, v117
	s_waitcnt lgkmcnt(2)
	v_mfma_f32_32x32x16_bf16 v[112:127], v[186:189], v[156:159], v[64:79]
	v_add_f32_e32 v100, v102, v100
	v_add_f32_e32 v101, v103, v101
	v_permlane32_swap_b32_e32 v96, v98
	v_permlane32_swap_b32_e32 v97, v99
	s_waitcnt lgkmcnt(1)
	v_mfma_f32_32x32x16_bf16 v[128:143], v[190:193], v[152:155], v[128:143]
	ds_read_b128 v[186:189], v185 offset:53248
	ds_read_b128 v[198:201], v185 offset:53760
	v_add_f32_e32 v100, v104, v100
	v_add_f32_e32 v101, v105, v101
	v_add_f32_e32 v202, v106, v100
	v_add_f32_e32 v203, v107, v101
	v_cvt_pk_bf16_f32 v100, v104, v105
	v_cvt_pk_bf16_f32 v101, v106, v107
	v_cvt_pk_bf16_f32 v102, v108, v109
	v_cvt_pk_bf16_f32 v103, v110, v111
	s_waitcnt lgkmcnt(2)
	v_mfma_f32_32x32x16_bf16 v[112:127], v[194:197], v[152:155], v[112:127]
	v_add_f32_e32 v104, v108, v202
	v_add_f32_e32 v105, v109, v203
	v_add_f32_e32 v190, v110, v104
	v_add_f32_e32 v191, v111, v105
	v_permlane32_swap_b32_e32 v100, v102
	v_permlane32_swap_b32_e32 v101, v103
	s_waitcnt lgkmcnt(1)
	v_mfma_f32_32x32x16_bf16 v[128:143], v[186:189], v[148:151], v[128:143]
	ds_read_b128 v[104:107], v185 offset:55296
	ds_read_b128 v[108:111], v185 offset:55808
	v_add_f32_e32 v185, v80, v190
	v_add_f32_e32 v190, v81, v191
	v_add_f32_e32 v185, v82, v185
	v_add_f32_e32 v190, v83, v190
	v_cvt_pk_bf16_f32 v80, v80, v81
	v_cvt_pk_bf16_f32 v81, v82, v83
	v_cvt_pk_bf16_f32 v82, v84, v85
	v_cvt_pk_bf16_f32 v83, v86, v87
	s_waitcnt lgkmcnt(2)
	v_mfma_f32_32x32x16_bf16 v[112:127], v[198:201], v[148:151], v[112:127]
	s_lshl_b32 s44, s38, 14
	v_add_u32_e32 v189, s44, v183
	ds_read_b64_tr_b16 v[194:195], v189 offset:0
	ds_read_b64_tr_b16 v[196:197], v189 offset:0x800
	ds_read_b64_tr_b16 v[198:199], v189 offset:0x1000
	ds_read_b64_tr_b16 v[200:201], v189 offset:0x1800
	ds_read_b64_tr_b16 v[190:191], v189 offset:0x2000
	ds_read_b64_tr_b16 v[192:193], v189 offset:0x2800
	v_add_f32_e32 v84, v84, v185
	v_add_f32_e32 v85, v85, v190
	v_add_f32_e32 v84, v86, v84
	v_add_f32_e32 v85, v87, v85
	v_permlane32_swap_b32_e32 v80, v82
	v_permlane32_swap_b32_e32 v81, v83
	s_waitcnt lgkmcnt(7)
	v_mfma_f32_32x32x16_bf16 v[128:143], v[104:107], v[144:147], v[128:143]
	ds_read_b64_tr_b16 v[212:213], v189 offset:0x3000
	ds_read_b64_tr_b16 v[214:215], v189 offset:0x3800
	ds_read_b64_tr_b16 v[216:217], v189 offset:0x200
	ds_read_b64_tr_b16 v[218:219], v189 offset:0xa00
	v_add_f32_e32 v84, v88, v84
	v_add_f32_e32 v85, v89, v85
	v_add_f32_e32 v185, v90, v84
	v_add_f32_e32 v186, v91, v85
	v_cvt_pk_bf16_f32 v84, v88, v89
	v_cvt_pk_bf16_f32 v85, v90, v91
	v_cvt_pk_bf16_f32 v86, v92, v93
	v_cvt_pk_bf16_f32 v87, v94, v95
	s_waitcnt lgkmcnt(10)
	v_mfma_f32_32x32x16_bf16 v[112:127], v[108:111], v[144:147], v[112:127]
	v_add_f32_e32 v88, v92, v185
	v_add_f32_e32 v89, v93, v186
	v_add_f32_e32 v88, v94, v88
	v_add_f32_e32 v89, v95, v89
	v_permlane32_swap_b32_e32 v84, v86
	v_permlane32_swap_b32_e32 v85, v87
	ds_read_b64_tr_b16 v[220:221], v189 offset:0x1200
	ds_read_b64_tr_b16 v[222:223], v189 offset:0x1a00
	ds_read_b64_tr_b16 v[224:225], v189 offset:0x2200
	ds_read_b64_tr_b16 v[226:227], v189 offset:0x2a00
	s_waitcnt lgkmcnt(12)
	v_mfma_f32_32x32x16_bf16 v[48:63], v[96:99], v[194:197], v[48:63]
	v_max_f32_e32 v90, v129, v129
	v_max_f32_e32 v91, v128, v128
	v_max_f32_e32 v90, v91, v90
	v_max3_f32 v91, v131, v132, v133
	v_max3_f32 v90, v90, v130, v134
	v_max3_f32 v91, v91, v136, v137
	ds_read_b64_tr_b16 v[194:195], v189 offset:0x3200
	ds_read_b64_tr_b16 v[196:197], v189 offset:0x3a00
	s_waitcnt lgkmcnt(12)
	v_mfma_f32_32x32x16_bf16 v[48:63], v[100:103], v[198:201], v[48:63]
	v_max3_f32 v90, v90, v135, v138
	v_max3_f32 v91, v91, v140, v141
	v_max3_f32 v90, v90, v139, v142
	v_max3_f32 v90, v90, v143, v91
	v_add_f32_e32 v186, v88, v89
	v_mov_b32_e32 v187, v186
	ds_read_b64_tr_b16 v[198:199], v189 offset:0x400
	ds_read_b64_tr_b16 v[200:201], v189 offset:0xc00
	s_waitcnt lgkmcnt(12)
	v_mfma_f32_32x32x16_bf16 v[48:63], v[80:83], v[190:193], v[48:63]
	v_max3_f32 v88, v112, v113, v114
	v_max3_f32 v89, v115, v116, v117
	v_max3_f32 v88, v88, v118, v119
	v_max3_f32 v89, v89, v120, v121
	v_permlane32_swap_b32_e32 v186, v187
	v_max3_f32 v88, v88, v122, v123
	ds_read_b64_tr_b16 v[190:191], v189 offset:0x1400
	ds_read_b64_tr_b16 v[192:193], v189 offset:0x1c00
	s_waitcnt lgkmcnt(12)
	v_mfma_f32_32x32x16_bf16 v[48:63], v[84:87], v[212:215], v[48:63]
	v_max3_f32 v89, v89, v124, v125
	v_max3_f32 v88, v88, v126, v127
	v_max3_f32 v88, v90, v88, v89
	v_mov_b32_e32 v89, v88
	ds_read_b64_tr_b16 v[212:213], v189 offset:0x2400
	ds_read_b64_tr_b16 v[214:215], v189 offset:0x2c00
	s_waitcnt lgkmcnt(12)
	v_mfma_f32_32x32x16_bf16 v[32:47], v[96:99], v[216:219], v[32:47]
	v_permlane32_swap_b32_e32 v88, v89
	v_max_f32_e32 v89, v89, v89
	v_max_f32_e32 v88, v88, v88
	v_max_f32_e32 v88, v88, v89
	v_cmp_lt_f32_e32 vcc, s47, v88
	v_mov_b32_e32 v188, 1.0
	s_cbranch_vccnz .LBB0_707
.Lattn_m0_res1:
	ds_read_b64_tr_b16 v[216:217], v189 offset:0x3400
	ds_read_b64_tr_b16 v[218:219], v189 offset:0x3c00
	s_waitcnt lgkmcnt(12)
	v_mfma_f32_32x32x16_bf16 v[32:47], v[100:103], v[220:223], v[32:47]
	v_exp_f32_e32 v128, v128
	v_exp_f32_e32 v129, v129
	v_exp_f32_e32 v130, v130
	ds_read_b64_tr_b16 v[220:221], v189 offset:0x600
	ds_read_b64_tr_b16 v[222:223], v189 offset:0xe00
	s_waitcnt lgkmcnt(12)
	v_mfma_f32_32x32x16_bf16 v[32:47], v[80:83], v[224:227], v[32:47]
	v_exp_f32_e32 v131, v131
	v_exp_f32_e32 v132, v132
	v_exp_f32_e32 v133, v133
	ds_read_b64_tr_b16 v[224:225], v189 offset:0x1600
	ds_read_b64_tr_b16 v[226:227], v189 offset:0x1e00
	s_waitcnt lgkmcnt(12)
	v_mfma_f32_32x32x16_bf16 v[32:47], v[84:87], v[194:197], v[32:47]
	v_exp_f32_e32 v134, v134
	v_exp_f32_e32 v135, v135
	v_exp_f32_e32 v136, v136
	ds_read_b64_tr_b16 v[194:195], v189 offset:0x2600
	ds_read_b64_tr_b16 v[196:197], v189 offset:0x2e00
	s_waitcnt lgkmcnt(12)
	v_mfma_f32_32x32x16_bf16 v[16:31], v[96:99], v[198:201], v[16:31]
	v_exp_f32_e32 v137, v137
	v_exp_f32_e32 v138, v138
	v_exp_f32_e32 v139, v139
	ds_read_b64_tr_b16 v[198:199], v189 offset:0x3600
	ds_read_b64_tr_b16 v[200:201], v189 offset:0x3e00
	s_waitcnt lgkmcnt(12)
	v_mfma_f32_32x32x16_bf16 v[16:31], v[100:103], v[190:193], v[16:31]
	v_exp_f32_e32 v140, v140
	v_exp_f32_e32 v141, v141
	v_exp_f32_e32 v142, v142
	s_waitcnt lgkmcnt(10)
	v_mfma_f32_32x32x16_bf16 v[16:31], v[80:83], v[212:215], v[16:31]
	v_exp_f32_e32 v143, v143
	v_exp_f32_e32 v112, v112
	v_exp_f32_e32 v113, v113
	s_waitcnt lgkmcnt(8)
	v_mfma_f32_32x32x16_bf16 v[16:31], v[84:87], v[216:219], v[16:31]
	v_exp_f32_e32 v114, v114
	v_exp_f32_e32 v115, v115
	v_exp_f32_e32 v116, v116
	s_waitcnt lgkmcnt(6)
	v_mfma_f32_32x32x16_bf16 v[0:15], v[96:99], v[220:223], v[0:15]
	v_exp_f32_e32 v117, v117
	v_exp_f32_e32 v118, v118
	v_exp_f32_e32 v119, v119
	s_waitcnt lgkmcnt(4)
	v_mfma_f32_32x32x16_bf16 v[0:15], v[100:103], v[224:227], v[0:15]
	v_exp_f32_e32 v120, v120
	v_exp_f32_e32 v121, v121
	v_exp_f32_e32 v122, v122
	s_waitcnt lgkmcnt(2)
	v_mfma_f32_32x32x16_bf16 v[0:15], v[80:83], v[194:197], v[0:15]
	v_exp_f32_e32 v123, v123
	v_exp_f32_e32 v124, v124
	v_exp_f32_e32 v125, v125
	s_waitcnt lgkmcnt(0)
	v_mfma_f32_32x32x16_bf16 v[0:15], v[84:87], v[198:201], v[0:15]
	v_exp_f32_e32 v126, v126
	v_exp_f32_e32 v127, v127
	v_cmp_gt_f32_e32 vcc, 1.0, v188
	s_cbranch_vccz .LBB0_700
	s_and_saveexec_b64 s[70:71], s[0:1]
	ds_write_b32 v177, v188 offset:128
	s_or_b64 exec, exec, s[70:71]
	s_waitcnt lgkmcnt(0)
	v_add_u32_e32 v92, s19, v168
	ds_read_b128 v[80:83], v92 offset:224
	ds_read_b128 v[84:87], v92 offset:192
	ds_read_b128 v[88:91], v92 offset:160
	ds_read_b128 v[92:95], v92 offset:128
	s_waitcnt lgkmcnt(3)
	v_pk_mul_f32 v[60:61], v[60:61], v[80:81]
	s_waitcnt lgkmcnt(2)
	v_pk_mul_f32 v[56:57], v[56:57], v[84:85]
	s_waitcnt lgkmcnt(1)
	v_pk_mul_f32 v[52:53], v[52:53], v[88:89]
	v_pk_mul_f32 v[62:63], v[62:63], v[82:83]
	v_pk_mul_f32 v[58:59], v[58:59], v[86:87]
	v_pk_mul_f32 v[54:55], v[54:55], v[90:91]
	s_waitcnt lgkmcnt(0)
	v_pk_mul_f32 v[50:51], v[50:51], v[94:95]
	v_pk_mul_f32 v[48:49], v[48:49], v[92:93]
	v_pk_mul_f32 v[44:45], v[44:45], v[80:81]
	v_pk_mul_f32 v[40:41], v[40:41], v[84:85]
	v_pk_mul_f32 v[36:37], v[36:37], v[88:89]
	v_pk_mul_f32 v[46:47], v[46:47], v[82:83]
	v_pk_mul_f32 v[42:43], v[42:43], v[86:87]
	v_pk_mul_f32 v[38:39], v[38:39], v[90:91]
	v_pk_mul_f32 v[34:35], v[34:35], v[94:95]
	v_pk_mul_f32 v[32:33], v[32:33], v[92:93]
	v_pk_mul_f32 v[28:29], v[28:29], v[80:81]
	v_pk_mul_f32 v[24:25], v[24:25], v[84:85]
	v_pk_mul_f32 v[20:21], v[20:21], v[88:89]
	v_pk_mul_f32 v[30:31], v[30:31], v[82:83]
	v_pk_mul_f32 v[26:27], v[26:27], v[86:87]
	v_pk_mul_f32 v[22:23], v[22:23], v[90:91]
	v_pk_mul_f32 v[18:19], v[18:19], v[94:95]
	v_pk_mul_f32 v[16:17], v[16:17], v[92:93]
	v_pk_mul_f32 v[12:13], v[12:13], v[80:81]
	v_pk_mul_f32 v[8:9], v[8:9], v[84:85]
	v_pk_mul_f32 v[4:5], v[4:5], v[88:89]
	v_pk_mul_f32 v[14:15], v[14:15], v[82:83]
	v_pk_mul_f32 v[10:11], v[10:11], v[86:87]
	v_pk_mul_f32 v[6:7], v[6:7], v[90:91]
	v_pk_mul_f32 v[2:3], v[2:3], v[94:95]
	v_pk_mul_f32 v[0:1], v[0:1], v[92:93]
.LBB0_700:
	s_add_u32 s48, s68, 0x20000
	s_addc_u32 s49, s69, 0
	s_lshl_b32 s45, s38, 13
	s_add_i32 s45, s45, s39
	s_waitcnt vmcnt(0) lgkmcnt(0)
	s_barrier
	v_add_u32_e32 v185, s43, v184
	ds_read_b128 v[80:83], v185 offset:49152
	ds_read_b128 v[190:193], v185 offset:49664
	s_mov_b32 m0, s45
	v_lshl_add_u64 v[212:213], v[172:173], 0, s[8:9]
	global_load_lds_dwordx4 v[212:213], off
	s_add_i32 s45, s44, s24
	s_mov_b32 m0, s45
	v_lshl_add_u64 v[214:215], s[48:49], 0, v[166:167]
	global_load_lds_dwordx4 v[214:215], off
	s_add_i32 s44, s44, s25
	s_mov_b32 m0, s44
	v_lshl_add_u64 v[212:213], s[48:49], 0, v[170:171]
	global_load_lds_dwordx4 v[212:213], off
	s_waitcnt lgkmcnt(1)
	v_mfma_f32_32x32x16_bf16 v[96:111], v[80:83], v[156:159], v[64:79]
	ds_read_b128 v[194:197], v185 offset:51200
	ds_read_b128 v[198:201], v185 offset:51712
	v_add_f32_e32 v84, 0, v128
	v_add_f32_e32 v85, 0, v129
	v_add_f32_e32 v84, v130, v84
	v_add_f32_e32 v85, v131, v85
	v_cvt_pk_bf16_f32 v128, v128, v129
	v_cvt_pk_bf16_f32 v129, v130, v131
	v_cvt_pk_bf16_f32 v130, v132, v133
	v_cvt_pk_bf16_f32 v131, v134, v135
	s_nop 0
	v_add_f32_e32 v80, v132, v84
	v_add_f32_e32 v81, v133, v85
	v_add_f32_e32 v132, v134, v80
	v_add_f32_e32 v133, v135, v81
	s_waitcnt lgkmcnt(2)
	v_mfma_f32_32x32x16_bf16 v[80:95], v[190:193], v[156:159], v[64:79]
	v_permlane32_swap_b32_e32 v128, v130
	v_permlane32_swap_b32_e32 v129, v131
	s_waitcnt lgkmcnt(1)
	v_mfma_f32_32x32x16_bf16 v[96:111], v[194:197], v[152:155], v[96:111]
	ds_read_b128 v[190:193], v185 offset:53248
	ds_read_b128 v[202:205], v185 offset:53760
	v_add_f32_e32 v132, v136, v132
	v_add_f32_e32 v133, v137, v133
	v_add_f32_e32 v189, v138, v132
	v_add_f32_e32 v206, v139, v133
	v_cvt_pk_bf16_f32 v132, v136, v137
	v_cvt_pk_bf16_f32 v133, v138, v139
	v_cvt_pk_bf16_f32 v134, v140, v141
	v_cvt_pk_bf16_f32 v135, v142, v143
	s_waitcnt lgkmcnt(2)
	v_mfma_f32_32x32x16_bf16 v[80:95], v[198:201], v[152:155], v[80:95]
	v_add_f32_e32 v136, v140, v189
	v_add_f32_e32 v137, v141, v206
	v_add_f32_e32 v189, v142, v136
	v_add_f32_e32 v194, v143, v137
	v_permlane32_swap_b32_e32 v132, v134
	v_permlane32_swap_b32_e32 v133, v135
	s_waitcnt lgkmcnt(1)
	v_mfma_f32_32x32x16_bf16 v[96:111], v[190:193], v[148:151], v[96:111]
	ds_read_b128 v[136:139], v185 offset:55296
	ds_read_b128 v[140:143], v185 offset:55808
	v_add_f32_e32 v185, v112, v189
	v_add_f32_e32 v189, v113, v194
	v_add_f32_e32 v185, v114, v185
	v_add_f32_e32 v189, v115, v189
	v_cvt_pk_bf16_f32 v112, v112, v113
	v_cvt_pk_bf16_f32 v113, v114, v115
	v_cvt_pk_bf16_f32 v114, v116, v117
	v_cvt_pk_bf16_f32 v115, v118, v119
	s_waitcnt lgkmcnt(2)
	v_mfma_f32_32x32x16_bf16 v[80:95], v[202:205], v[148:151], v[80:95]
	v_lshl_add_u32 v206, s42, 14, v183
	ds_read_b64_tr_b16 v[198:199], v206 offset:0
	ds_read_b64_tr_b16 v[200:201], v206 offset:0x800
	ds_read_b64_tr_b16 v[190:191], v206 offset:0x1000
	ds_read_b64_tr_b16 v[192:193], v206 offset:0x1800
	ds_read_b64_tr_b16 v[202:203], v206 offset:0x2000
	ds_read_b64_tr_b16 v[204:205], v206 offset:0x2800
	v_add_f32_e32 v116, v116, v185
	v_add_f32_e32 v117, v117, v189
	v_add_f32_e32 v116, v118, v116
	v_add_f32_e32 v117, v119, v117
	v_permlane32_swap_b32_e32 v112, v114
	v_permlane32_swap_b32_e32 v113, v115
	s_waitcnt lgkmcnt(7)
	v_mfma_f32_32x32x16_bf16 v[96:111], v[136:139], v[144:147], v[96:111]
	ds_read_b64_tr_b16 v[212:213], v206 offset:0x3000
	ds_read_b64_tr_b16 v[214:215], v206 offset:0x3800
	ds_read_b64_tr_b16 v[216:217], v206 offset:0x200
	ds_read_b64_tr_b16 v[218:219], v206 offset:0xa00
	v_add_f32_e32 v116, v120, v116
	v_add_f32_e32 v117, v121, v117
	v_add_f32_e32 v185, v122, v116
	v_add_f32_e32 v189, v123, v117
	v_cvt_pk_bf16_f32 v116, v120, v121
	v_cvt_pk_bf16_f32 v117, v122, v123
	v_cvt_pk_bf16_f32 v118, v124, v125
	v_cvt_pk_bf16_f32 v119, v126, v127
	s_waitcnt lgkmcnt(10)
	v_mfma_f32_32x32x16_bf16 v[80:95], v[140:143], v[144:147], v[80:95]
	v_add_f32_e32 v120, v124, v185
	v_add_f32_e32 v121, v125, v189
	v_add_f32_e32 v120, v126, v120
	v_add_f32_e32 v121, v127, v121
	v_permlane32_swap_b32_e32 v116, v118
	v_permlane32_swap_b32_e32 v117, v119
	ds_read_b64_tr_b16 v[220:221], v206 offset:0x1200
	ds_read_b64_tr_b16 v[222:223], v206 offset:0x1a00
	ds_read_b64_tr_b16 v[224:225], v206 offset:0x2200
	ds_read_b64_tr_b16 v[226:227], v206 offset:0x2a00
	s_waitcnt lgkmcnt(12)
	v_mfma_f32_32x32x16_bf16 v[48:63], v[128:131], v[198:201], v[48:63]
	v_max_f32_e32 v122, v97, v97
	v_max_f32_e32 v123, v96, v96
	v_max_f32_e32 v122, v123, v122
	v_max3_f32 v123, v99, v100, v101
	v_max3_f32 v122, v122, v98, v102
	v_max3_f32 v123, v123, v104, v105
	ds_read_b64_tr_b16 v[198:199], v206 offset:0x3200
	ds_read_b64_tr_b16 v[200:201], v206 offset:0x3a00
	s_waitcnt lgkmcnt(12)
	v_mfma_f32_32x32x16_bf16 v[48:63], v[132:135], v[190:193], v[48:63]
	v_max3_f32 v122, v122, v103, v106
	v_max3_f32 v123, v123, v108, v109
	v_max3_f32 v122, v122, v107, v110
	v_max3_f32 v122, v122, v111, v123
	v_add_f32_e32 v120, v120, v121
	v_mov_b32_e32 v121, v120
	ds_read_b64_tr_b16 v[190:191], v206 offset:0x400
	ds_read_b64_tr_b16 v[192:193], v206 offset:0xc00
	s_waitcnt lgkmcnt(12)
	v_mfma_f32_32x32x16_bf16 v[48:63], v[112:115], v[202:205], v[48:63]
	v_max3_f32 v123, v80, v81, v82
	v_max3_f32 v124, v83, v84, v85
	v_max3_f32 v123, v123, v86, v87
	v_max3_f32 v124, v124, v88, v89
	v_permlane32_swap_b32_e32 v120, v121
	v_max3_f32 v123, v123, v90, v91
	ds_read_b64_tr_b16 v[202:203], v206 offset:0x1400
	ds_read_b64_tr_b16 v[204:205], v206 offset:0x1c00
	s_waitcnt lgkmcnt(12)
	v_mfma_f32_32x32x16_bf16 v[48:63], v[116:119], v[212:215], v[48:63]
	v_max3_f32 v124, v124, v92, v93
	v_max3_f32 v123, v123, v94, v95
	v_max3_f32 v122, v122, v123, v124
	v_mov_b32_e32 v123, v122
	ds_read_b64_tr_b16 v[212:213], v206 offset:0x2400
	ds_read_b64_tr_b16 v[214:215], v206 offset:0x2c00
	s_waitcnt lgkmcnt(12)
	v_mfma_f32_32x32x16_bf16 v[32:47], v[128:131], v[216:219], v[32:47]
	v_permlane32_swap_b32_e32 v122, v123
	v_max_f32_e32 v123, v123, v123
	v_max_f32_e32 v122, v122, v122
	v_max_f32_e32 v122, v122, v123
	v_cmp_lt_f32_e32 vcc, s47, v122
	v_mov_b32_e32 v185, 1.0
	s_cbranch_vccnz .LBB0_708
.Lattn_m0_res2:
	ds_read_b64_tr_b16 v[216:217], v206 offset:0x3400
	ds_read_b64_tr_b16 v[218:219], v206 offset:0x3c00
	s_waitcnt lgkmcnt(12)
	v_mfma_f32_32x32x16_bf16 v[32:47], v[132:135], v[220:223], v[32:47]
	v_exp_f32_e32 v96, v96
	v_exp_f32_e32 v97, v97
	v_exp_f32_e32 v98, v98
	ds_read_b64_tr_b16 v[220:221], v206 offset:0x600
	ds_read_b64_tr_b16 v[222:223], v206 offset:0xe00
	s_waitcnt lgkmcnt(12)
	v_mfma_f32_32x32x16_bf16 v[32:47], v[112:115], v[224:227], v[32:47]
	v_exp_f32_e32 v99, v99
	v_exp_f32_e32 v100, v100
	v_exp_f32_e32 v101, v101
	ds_read_b64_tr_b16 v[224:225], v206 offset:0x1600
	ds_read_b64_tr_b16 v[226:227], v206 offset:0x1e00
	s_waitcnt lgkmcnt(12)
	v_mfma_f32_32x32x16_bf16 v[32:47], v[116:119], v[198:201], v[32:47]
	v_exp_f32_e32 v102, v102
	v_exp_f32_e32 v103, v103
	v_exp_f32_e32 v104, v104
	ds_read_b64_tr_b16 v[198:199], v206 offset:0x2600
	ds_read_b64_tr_b16 v[200:201], v206 offset:0x2e00
	s_waitcnt lgkmcnt(12)
	v_mfma_f32_32x32x16_bf16 v[16:31], v[128:131], v[190:193], v[16:31]
	v_exp_f32_e32 v105, v105
	v_exp_f32_e32 v106, v106
	v_exp_f32_e32 v107, v107
	ds_read_b64_tr_b16 v[190:191], v206 offset:0x3600
	ds_read_b64_tr_b16 v[192:193], v206 offset:0x3e00
	s_waitcnt lgkmcnt(12)
	v_mfma_f32_32x32x16_bf16 v[16:31], v[132:135], v[202:205], v[16:31]
	v_exp_f32_e32 v108, v108
	v_exp_f32_e32 v109, v109
	v_exp_f32_e32 v110, v110
	s_waitcnt lgkmcnt(10)
	v_mfma_f32_32x32x16_bf16 v[16:31], v[112:115], v[212:215], v[16:31]
	v_exp_f32_e32 v111, v111
	v_exp_f32_e32 v80, v80
	v_exp_f32_e32 v81, v81
	s_waitcnt lgkmcnt(8)
	v_mfma_f32_32x32x16_bf16 v[16:31], v[116:119], v[216:219], v[16:31]
	v_exp_f32_e32 v82, v82
	v_exp_f32_e32 v83, v83
	v_exp_f32_e32 v84, v84
	s_waitcnt lgkmcnt(6)
	v_mfma_f32_32x32x16_bf16 v[0:15], v[128:131], v[220:223], v[0:15]
	v_exp_f32_e32 v85, v85
	v_exp_f32_e32 v86, v86
	v_exp_f32_e32 v87, v87
	s_waitcnt lgkmcnt(4)
	v_mfma_f32_32x32x16_bf16 v[0:15], v[132:135], v[224:227], v[0:15]
	v_exp_f32_e32 v88, v88
	v_exp_f32_e32 v89, v89
	v_exp_f32_e32 v90, v90
	s_waitcnt lgkmcnt(2)
	v_mfma_f32_32x32x16_bf16 v[0:15], v[112:115], v[198:201], v[0:15]
	v_exp_f32_e32 v91, v91
	v_exp_f32_e32 v92, v92
	v_exp_f32_e32 v93, v93
	s_waitcnt lgkmcnt(0)
	v_mfma_f32_32x32x16_bf16 v[0:15], v[116:119], v[190:193], v[0:15]
	v_exp_f32_e32 v94, v94
	v_exp_f32_e32 v95, v95
	v_cmp_gt_f32_e32 vcc, 1.0, v185
	s_cbranch_vccz .LBB0_705
	s_and_saveexec_b64 s[70:71], s[0:1]
	ds_write_b32 v177, v185 offset:128
	s_or_b64 exec, exec, s[70:71]
	s_waitcnt lgkmcnt(0)
	v_add_u32_e32 v126, s19, v168
	ds_read_b128 v[112:115], v126 offset:224
	ds_read_b128 v[116:119], v126 offset:192
	ds_read_b128 v[122:125], v126 offset:160
	ds_read_b128 v[126:129], v126 offset:128
	s_waitcnt lgkmcnt(3)
	v_pk_mul_f32 v[60:61], v[60:61], v[112:113]
	s_waitcnt lgkmcnt(2)
	v_pk_mul_f32 v[56:57], v[56:57], v[116:117]
	s_waitcnt lgkmcnt(1)
	v_pk_mul_f32 v[52:53], v[52:53], v[122:123]
	v_pk_mul_f32 v[62:63], v[62:63], v[114:115]
	v_pk_mul_f32 v[58:59], v[58:59], v[118:119]
	v_pk_mul_f32 v[54:55], v[54:55], v[124:125]
	s_waitcnt lgkmcnt(0)
	v_pk_mul_f32 v[50:51], v[50:51], v[128:129]
	v_pk_mul_f32 v[48:49], v[48:49], v[126:127]
	v_pk_mul_f32 v[44:45], v[44:45], v[112:113]
	v_pk_mul_f32 v[40:41], v[40:41], v[116:117]
	v_pk_mul_f32 v[36:37], v[36:37], v[122:123]
	v_pk_mul_f32 v[46:47], v[46:47], v[114:115]
	v_pk_mul_f32 v[42:43], v[42:43], v[118:119]
	v_pk_mul_f32 v[38:39], v[38:39], v[124:125]
	v_pk_mul_f32 v[34:35], v[34:35], v[128:129]
	v_pk_mul_f32 v[32:33], v[32:33], v[126:127]
	v_pk_mul_f32 v[28:29], v[28:29], v[112:113]
	v_pk_mul_f32 v[24:25], v[24:25], v[116:117]
	v_pk_mul_f32 v[20:21], v[20:21], v[122:123]
	v_pk_mul_f32 v[30:31], v[30:31], v[114:115]
	v_pk_mul_f32 v[26:27], v[26:27], v[118:119]
	v_pk_mul_f32 v[22:23], v[22:23], v[124:125]
	v_pk_mul_f32 v[18:19], v[18:19], v[128:129]
	v_pk_mul_f32 v[16:17], v[16:17], v[126:127]
	v_pk_mul_f32 v[12:13], v[12:13], v[112:113]
	v_pk_mul_f32 v[8:9], v[8:9], v[116:117]
	v_pk_mul_f32 v[4:5], v[4:5], v[122:123]
	v_pk_mul_f32 v[14:15], v[14:15], v[114:115]
	v_pk_mul_f32 v[10:11], v[10:11], v[118:119]
	v_pk_mul_f32 v[6:7], v[6:7], v[124:125]
	v_pk_mul_f32 v[2:3], v[2:3], v[128:129]
	v_pk_mul_f32 v[0:1], v[0:1], v[126:127]

.LBB0_720:
	s_lshl_b32 s43, s34, 13
	s_mov_b32 s42, s38
	v_lshl_add_u32 v187, s42, 13, v186
	ds_read_b128 v[112:115], v187 offset:49152
	ds_read_b128 v[188:191], v187 offset:49664
	s_add_i32 s38, s43, s39
	s_mov_b32 m0, s38
	v_lshl_add_u64 v[212:213], s[4:5], 0, v[166:167]
	global_load_lds_dwordx4 v[172:173], off
	s_lshl_b32 s38, s34, 14
	s_add_i32 s45, s38, s24
	s_mov_b32 m0, s45
	v_lshl_add_u64 v[214:215], s[4:5], 0, v[170:171]
	global_load_lds_dwordx4 v[212:213], off
	s_add_i32 s38, s38, s25
	s_mov_b32 m0, s38
	s_mov_b32 s38, s44
	global_load_lds_dwordx4 v[214:215], off
	s_waitcnt lgkmcnt(1)
	v_mfma_f32_32x32x16_bf16 v[128:143], v[112:115], v[156:159], v[64:79]
	ds_read_b128 v[192:195], v187 offset:51200
	ds_read_b128 v[196:199], v187 offset:51712
	v_add_f32_e32 v116, 0, v96
	v_add_f32_e32 v117, 0, v97
	v_add_f32_e32 v116, v98, v116
	v_add_f32_e32 v117, v99, v117
	v_cvt_pk_bf16_f32 v96, v96, v97
	v_cvt_pk_bf16_f32 v97, v98, v99
	v_cvt_pk_bf16_f32 v98, v100, v101
	v_cvt_pk_bf16_f32 v99, v102, v103
	s_nop 0
	v_add_f32_e32 v100, v100, v116
	v_add_f32_e32 v101, v101, v117
	s_waitcnt lgkmcnt(2)
	v_mfma_f32_32x32x16_bf16 v[112:127], v[188:191], v[156:159], v[64:79]
	v_add_f32_e32 v100, v102, v100
	v_add_f32_e32 v101, v103, v101
	v_permlane32_swap_b32_e32 v96, v98
	v_permlane32_swap_b32_e32 v97, v99
	s_waitcnt lgkmcnt(1)
	v_mfma_f32_32x32x16_bf16 v[128:143], v[192:195], v[152:155], v[128:143]
	ds_read_b128 v[188:191], v187 offset:53248
	ds_read_b128 v[200:203], v187 offset:53760
	v_add_f32_e32 v100, v104, v100
	v_add_f32_e32 v101, v105, v101
	v_add_f32_e32 v204, v106, v100
	v_add_f32_e32 v205, v107, v101
	v_cvt_pk_bf16_f32 v100, v104, v105
	v_cvt_pk_bf16_f32 v101, v106, v107
	v_cvt_pk_bf16_f32 v102, v108, v109
	v_cvt_pk_bf16_f32 v103, v110, v111
	s_waitcnt lgkmcnt(2)
	v_mfma_f32_32x32x16_bf16 v[112:127], v[196:199], v[152:155], v[112:127]
	v_add_f32_e32 v104, v108, v204
	v_add_f32_e32 v105, v109, v205
	v_add_f32_e32 v192, v110, v104
	v_add_f32_e32 v193, v111, v105
	v_permlane32_swap_b32_e32 v100, v102
	v_permlane32_swap_b32_e32 v101, v103
	s_waitcnt lgkmcnt(1)
	v_mfma_f32_32x32x16_bf16 v[128:143], v[188:191], v[148:151], v[128:143]
	ds_read_b128 v[104:107], v187 offset:55296
	ds_read_b128 v[108:111], v187 offset:55808
	v_add_f32_e32 v187, v80, v192
	v_add_f32_e32 v192, v81, v193
	v_add_f32_e32 v187, v82, v187
	v_add_f32_e32 v192, v83, v192
	v_cvt_pk_bf16_f32 v80, v80, v81
	v_cvt_pk_bf16_f32 v81, v82, v83
	v_cvt_pk_bf16_f32 v82, v84, v85
	v_cvt_pk_bf16_f32 v83, v86, v87
	s_waitcnt lgkmcnt(2)
	v_mfma_f32_32x32x16_bf16 v[112:127], v[200:203], v[148:151], v[112:127]
	s_lshl_b32 s44, s38, 14
	v_add_u32_e32 v191, s44, v185
	ds_read_b64_tr_b16 v[196:197], v191 offset:0
	ds_read_b64_tr_b16 v[198:199], v191 offset:0x800
	ds_read_b64_tr_b16 v[200:201], v191 offset:0x1000
	ds_read_b64_tr_b16 v[202:203], v191 offset:0x1800
	ds_read_b64_tr_b16 v[192:193], v191 offset:0x2000
	ds_read_b64_tr_b16 v[194:195], v191 offset:0x2800
	v_add_f32_e32 v84, v84, v187
	v_add_f32_e32 v85, v85, v192
	v_add_f32_e32 v84, v86, v84
	v_add_f32_e32 v85, v87, v85
	v_permlane32_swap_b32_e32 v80, v82
	v_permlane32_swap_b32_e32 v81, v83
	s_waitcnt lgkmcnt(7)
	v_mfma_f32_32x32x16_bf16 v[128:143], v[104:107], v[144:147], v[128:143]
	ds_read_b64_tr_b16 v[212:213], v191 offset:0x3000
	ds_read_b64_tr_b16 v[214:215], v191 offset:0x3800
	ds_read_b64_tr_b16 v[216:217], v191 offset:0x200
	ds_read_b64_tr_b16 v[218:219], v191 offset:0xa00
	v_add_f32_e32 v84, v88, v84
	v_add_f32_e32 v85, v89, v85
	v_add_f32_e32 v187, v90, v84
	v_add_f32_e32 v188, v91, v85
	v_cvt_pk_bf16_f32 v84, v88, v89
	v_cvt_pk_bf16_f32 v85, v90, v91
	v_cvt_pk_bf16_f32 v86, v92, v93
	v_cvt_pk_bf16_f32 v87, v94, v95
	s_waitcnt lgkmcnt(10)
	v_mfma_f32_32x32x16_bf16 v[112:127], v[108:111], v[144:147], v[112:127]
	v_add_f32_e32 v88, v92, v187
	v_add_f32_e32 v89, v93, v188
	v_add_f32_e32 v88, v94, v88
	v_add_f32_e32 v89, v95, v89
	v_permlane32_swap_b32_e32 v84, v86
	v_permlane32_swap_b32_e32 v85, v87
	ds_read_b64_tr_b16 v[220:221], v191 offset:0x1200
	ds_read_b64_tr_b16 v[222:223], v191 offset:0x1a00
	ds_read_b64_tr_b16 v[224:225], v191 offset:0x2200
	ds_read_b64_tr_b16 v[226:227], v191 offset:0x2a00
	s_waitcnt lgkmcnt(12)
	v_mfma_f32_32x32x16_bf16 v[48:63], v[96:99], v[196:199], v[48:63]
	v_max_f32_e32 v90, v129, v129
	v_max_f32_e32 v91, v128, v128
	v_max_f32_e32 v90, v91, v90
	v_max3_f32 v91, v131, v132, v133
	v_max3_f32 v90, v90, v130, v134
	v_max3_f32 v91, v91, v136, v137
	ds_read_b64_tr_b16 v[196:197], v191 offset:0x3200
	ds_read_b64_tr_b16 v[198:199], v191 offset:0x3a00
	s_waitcnt lgkmcnt(12)
	v_mfma_f32_32x32x16_bf16 v[48:63], v[100:103], v[200:203], v[48:63]
	v_max3_f32 v90, v90, v135, v138
	v_max3_f32 v91, v91, v140, v141
	v_max3_f32 v90, v90, v139, v142
	v_max3_f32 v90, v90, v143, v91
	v_add_f32_e32 v188, v88, v89
	v_mov_b32_e32 v189, v188
	ds_read_b64_tr_b16 v[200:201], v191 offset:0x400
	ds_read_b64_tr_b16 v[202:203], v191 offset:0xc00
	s_waitcnt lgkmcnt(12)
	v_mfma_f32_32x32x16_bf16 v[48:63], v[80:83], v[192:195], v[48:63]
	v_max3_f32 v88, v112, v113, v114
	v_max3_f32 v89, v115, v116, v117
	v_max3_f32 v88, v88, v118, v119
	v_max3_f32 v89, v89, v120, v121
	v_permlane32_swap_b32_e32 v188, v189
	v_max3_f32 v88, v88, v122, v123
	ds_read_b64_tr_b16 v[192:193], v191 offset:0x1400
	ds_read_b64_tr_b16 v[194:195], v191 offset:0x1c00
	s_waitcnt lgkmcnt(12)
	v_mfma_f32_32x32x16_bf16 v[48:63], v[84:87], v[212:215], v[48:63]
	v_max3_f32 v89, v89, v124, v125
	v_max3_f32 v88, v88, v126, v127
	v_max3_f32 v88, v90, v88, v89
	v_mov_b32_e32 v89, v88
	ds_read_b64_tr_b16 v[212:213], v191 offset:0x2400
	ds_read_b64_tr_b16 v[214:215], v191 offset:0x2c00
	s_waitcnt lgkmcnt(12)
	v_mfma_f32_32x32x16_bf16 v[32:47], v[96:99], v[216:219], v[32:47]
	v_permlane32_swap_b32_e32 v88, v89
	v_max_f32_e32 v89, v89, v89
	v_max_f32_e32 v88, v88, v88
	v_max_f32_e32 v88, v88, v89
	v_cmp_lt_f32_e32 vcc, s47, v88
	v_mov_b32_e32 v190, 1.0
	s_cbranch_vccnz .LBB0_732
.Lattn_m1_res1:
	ds_read_b64_tr_b16 v[216:217], v191 offset:0x3400
	ds_read_b64_tr_b16 v[218:219], v191 offset:0x3c00
	s_waitcnt lgkmcnt(12)
	v_mfma_f32_32x32x16_bf16 v[32:47], v[100:103], v[220:223], v[32:47]
	v_exp_f32_e32 v128, v128
	v_exp_f32_e32 v129, v129
	v_exp_f32_e32 v130, v130
	ds_read_b64_tr_b16 v[220:221], v191 offset:0x600
	ds_read_b64_tr_b16 v[222:223], v191 offset:0xe00
	s_waitcnt lgkmcnt(12)
	v_mfma_f32_32x32x16_bf16 v[32:47], v[80:83], v[224:227], v[32:47]
	v_exp_f32_e32 v131, v131
	v_exp_f32_e32 v132, v132
	v_exp_f32_e32 v133, v133
	ds_read_b64_tr_b16 v[224:225], v191 offset:0x1600
	ds_read_b64_tr_b16 v[226:227], v191 offset:0x1e00
	s_waitcnt lgkmcnt(12)
	v_mfma_f32_32x32x16_bf16 v[32:47], v[84:87], v[196:199], v[32:47]
	v_exp_f32_e32 v134, v134
	v_exp_f32_e32 v135, v135
	v_exp_f32_e32 v136, v136
	ds_read_b64_tr_b16 v[196:197], v191 offset:0x2600
	ds_read_b64_tr_b16 v[198:199], v191 offset:0x2e00
	s_waitcnt lgkmcnt(12)
	v_mfma_f32_32x32x16_bf16 v[16:31], v[96:99], v[200:203], v[16:31]
	v_exp_f32_e32 v137, v137
	v_exp_f32_e32 v138, v138
	v_exp_f32_e32 v139, v139
	ds_read_b64_tr_b16 v[200:201], v191 offset:0x3600
	ds_read_b64_tr_b16 v[202:203], v191 offset:0x3e00
	s_waitcnt lgkmcnt(12)
	v_mfma_f32_32x32x16_bf16 v[16:31], v[100:103], v[192:195], v[16:31]
	v_exp_f32_e32 v140, v140
	v_exp_f32_e32 v141, v141
	v_exp_f32_e32 v142, v142
	s_waitcnt lgkmcnt(10)
	v_mfma_f32_32x32x16_bf16 v[16:31], v[80:83], v[212:215], v[16:31]
	v_exp_f32_e32 v143, v143
	v_exp_f32_e32 v112, v112
	v_exp_f32_e32 v113, v113
	s_waitcnt lgkmcnt(8)
	v_mfma_f32_32x32x16_bf16 v[16:31], v[84:87], v[216:219], v[16:31]
	v_exp_f32_e32 v114, v114
	v_exp_f32_e32 v115, v115
	v_exp_f32_e32 v116, v116
	s_waitcnt lgkmcnt(6)
	v_mfma_f32_32x32x16_bf16 v[0:15], v[96:99], v[220:223], v[0:15]
	v_exp_f32_e32 v117, v117
	v_exp_f32_e32 v118, v118
	v_exp_f32_e32 v119, v119
	s_waitcnt lgkmcnt(4)
	v_mfma_f32_32x32x16_bf16 v[0:15], v[100:103], v[224:227], v[0:15]
	v_exp_f32_e32 v120, v120
	v_exp_f32_e32 v121, v121
	v_exp_f32_e32 v122, v122
	s_waitcnt lgkmcnt(2)
	v_mfma_f32_32x32x16_bf16 v[0:15], v[80:83], v[196:199], v[0:15]
	v_exp_f32_e32 v123, v123
	v_exp_f32_e32 v124, v124
	v_exp_f32_e32 v125, v125
	s_waitcnt lgkmcnt(0)
	v_mfma_f32_32x32x16_bf16 v[0:15], v[84:87], v[200:203], v[0:15]
	v_exp_f32_e32 v126, v126
	v_exp_f32_e32 v127, v127
	v_cmp_gt_f32_e32 vcc, 1.0, v190
	s_cbranch_vccz .LBB0_725
	s_and_saveexec_b64 s[52:53], s[0:1]
	ds_write_b32 v180, v190 offset:128
	s_or_b64 exec, exec, s[52:53]
	s_waitcnt lgkmcnt(0)
	v_add_u32_e32 v92, s19, v168
	ds_read_b128 v[80:83], v92 offset:224
	ds_read_b128 v[84:87], v92 offset:192
	ds_read_b128 v[88:91], v92 offset:160
	ds_read_b128 v[92:95], v92 offset:128
	s_waitcnt lgkmcnt(3)
	v_pk_mul_f32 v[60:61], v[60:61], v[80:81]
	s_waitcnt lgkmcnt(2)
	v_pk_mul_f32 v[56:57], v[56:57], v[84:85]
	s_waitcnt lgkmcnt(1)
	v_pk_mul_f32 v[52:53], v[52:53], v[88:89]
	v_pk_mul_f32 v[62:63], v[62:63], v[82:83]
	v_pk_mul_f32 v[58:59], v[58:59], v[86:87]
	v_pk_mul_f32 v[54:55], v[54:55], v[90:91]
	s_waitcnt lgkmcnt(0)
	v_pk_mul_f32 v[50:51], v[50:51], v[94:95]
	v_pk_mul_f32 v[48:49], v[48:49], v[92:93]
	v_pk_mul_f32 v[44:45], v[44:45], v[80:81]
	v_pk_mul_f32 v[40:41], v[40:41], v[84:85]
	v_pk_mul_f32 v[36:37], v[36:37], v[88:89]
	v_pk_mul_f32 v[46:47], v[46:47], v[82:83]
	v_pk_mul_f32 v[42:43], v[42:43], v[86:87]
	v_pk_mul_f32 v[38:39], v[38:39], v[90:91]
	v_pk_mul_f32 v[34:35], v[34:35], v[94:95]
	v_pk_mul_f32 v[32:33], v[32:33], v[92:93]
	v_pk_mul_f32 v[28:29], v[28:29], v[80:81]
	v_pk_mul_f32 v[24:25], v[24:25], v[84:85]
	v_pk_mul_f32 v[20:21], v[20:21], v[88:89]
	v_pk_mul_f32 v[30:31], v[30:31], v[82:83]
	v_pk_mul_f32 v[26:27], v[26:27], v[86:87]
	v_pk_mul_f32 v[22:23], v[22:23], v[90:91]
	v_pk_mul_f32 v[18:19], v[18:19], v[94:95]
	v_pk_mul_f32 v[16:17], v[16:17], v[92:93]
	v_pk_mul_f32 v[12:13], v[12:13], v[80:81]
	v_pk_mul_f32 v[8:9], v[8:9], v[84:85]
	v_pk_mul_f32 v[4:5], v[4:5], v[88:89]
	v_pk_mul_f32 v[14:15], v[14:15], v[82:83]
	v_pk_mul_f32 v[10:11], v[10:11], v[86:87]
	v_pk_mul_f32 v[6:7], v[6:7], v[90:91]
	v_pk_mul_f32 v[2:3], v[2:3], v[94:95]
	v_pk_mul_f32 v[0:1], v[0:1], v[92:93]
.LBB0_725:
	s_add_u32 s48, s4, 0x20000
	s_addc_u32 s49, s5, 0
	s_lshl_b32 s45, s38, 13
	s_add_i32 s45, s45, s39
	s_waitcnt vmcnt(0) lgkmcnt(0)
	s_barrier
	v_add_u32_e32 v187, s43, v186
	ds_read_b128 v[80:83], v187 offset:49152
	ds_read_b128 v[192:195], v187 offset:49664
	s_mov_b32 m0, s45
	v_lshl_add_u64 v[212:213], v[172:173], 0, s[8:9]
	global_load_lds_dwordx4 v[212:213], off
	s_add_i32 s45, s44, s24
	s_mov_b32 m0, s45
	v_lshl_add_u64 v[214:215], s[48:49], 0, v[166:167]
	global_load_lds_dwordx4 v[214:215], off
	s_add_i32 s44, s44, s25
	s_mov_b32 m0, s44
	v_lshl_add_u64 v[212:213], s[48:49], 0, v[170:171]
	global_load_lds_dwordx4 v[212:213], off
	s_waitcnt lgkmcnt(1)
	v_mfma_f32_32x32x16_bf16 v[96:111], v[80:83], v[156:159], v[64:79]
	ds_read_b128 v[196:199], v187 offset:51200
	ds_read_b128 v[200:203], v187 offset:51712
	v_add_f32_e32 v84, 0, v128
	v_add_f32_e32 v85, 0, v129
	v_add_f32_e32 v84, v130, v84
	v_add_f32_e32 v85, v131, v85
	v_cvt_pk_bf16_f32 v128, v128, v129
	v_cvt_pk_bf16_f32 v129, v130, v131
	v_cvt_pk_bf16_f32 v130, v132, v133
	v_cvt_pk_bf16_f32 v131, v134, v135
	s_nop 0
	v_add_f32_e32 v80, v132, v84
	v_add_f32_e32 v81, v133, v85
	v_add_f32_e32 v132, v134, v80
	v_add_f32_e32 v133, v135, v81
	s_waitcnt lgkmcnt(2)
	v_mfma_f32_32x32x16_bf16 v[80:95], v[192:195], v[156:159], v[64:79]
	v_permlane32_swap_b32_e32 v128, v130
	v_permlane32_swap_b32_e32 v129, v131
	s_waitcnt lgkmcnt(1)
	v_mfma_f32_32x32x16_bf16 v[96:111], v[196:199], v[152:155], v[96:111]
	ds_read_b128 v[192:195], v187 offset:53248
	ds_read_b128 v[204:207], v187 offset:53760
	v_add_f32_e32 v132, v136, v132
	v_add_f32_e32 v133, v137, v133
	v_add_f32_e32 v191, v138, v132
	v_add_f32_e32 v208, v139, v133
	v_cvt_pk_bf16_f32 v132, v136, v137
	v_cvt_pk_bf16_f32 v133, v138, v139
	v_cvt_pk_bf16_f32 v134, v140, v141
	v_cvt_pk_bf16_f32 v135, v142, v143
	s_waitcnt lgkmcnt(2)
	v_mfma_f32_32x32x16_bf16 v[80:95], v[200:203], v[152:155], v[80:95]
	v_add_f32_e32 v136, v140, v191
	v_add_f32_e32 v137, v141, v208
	v_add_f32_e32 v191, v142, v136
	v_add_f32_e32 v196, v143, v137
	v_permlane32_swap_b32_e32 v132, v134
	v_permlane32_swap_b32_e32 v133, v135
	s_waitcnt lgkmcnt(1)
	v_mfma_f32_32x32x16_bf16 v[96:111], v[192:195], v[148:151], v[96:111]
	ds_read_b128 v[136:139], v187 offset:55296
	ds_read_b128 v[140:143], v187 offset:55808
	v_add_f32_e32 v187, v112, v191
	v_add_f32_e32 v191, v113, v196
	v_add_f32_e32 v187, v114, v187
	v_add_f32_e32 v191, v115, v191
	v_cvt_pk_bf16_f32 v112, v112, v113
	v_cvt_pk_bf16_f32 v113, v114, v115
	v_cvt_pk_bf16_f32 v114, v116, v117
	v_cvt_pk_bf16_f32 v115, v118, v119
	s_waitcnt lgkmcnt(2)
	v_mfma_f32_32x32x16_bf16 v[80:95], v[204:207], v[148:151], v[80:95]
	v_lshl_add_u32 v208, s42, 14, v185
	ds_read_b64_tr_b16 v[200:201], v208 offset:0
	ds_read_b64_tr_b16 v[202:203], v208 offset:0x800
	ds_read_b64_tr_b16 v[192:193], v208 offset:0x1000
	ds_read_b64_tr_b16 v[194:195], v208 offset:0x1800
	ds_read_b64_tr_b16 v[204:205], v208 offset:0x2000
	ds_read_b64_tr_b16 v[206:207], v208 offset:0x2800
	v_add_f32_e32 v116, v116, v187
	v_add_f32_e32 v117, v117, v191
	v_add_f32_e32 v116, v118, v116
	v_add_f32_e32 v117, v119, v117
	v_permlane32_swap_b32_e32 v112, v114
	v_permlane32_swap_b32_e32 v113, v115
	s_waitcnt lgkmcnt(7)
	v_mfma_f32_32x32x16_bf16 v[96:111], v[136:139], v[144:147], v[96:111]
	ds_read_b64_tr_b16 v[212:213], v208 offset:0x3000
	ds_read_b64_tr_b16 v[214:215], v208 offset:0x3800
	ds_read_b64_tr_b16 v[216:217], v208 offset:0x200
	ds_read_b64_tr_b16 v[218:219], v208 offset:0xa00
	v_add_f32_e32 v116, v120, v116
	v_add_f32_e32 v117, v121, v117
	v_add_f32_e32 v187, v122, v116
	v_add_f32_e32 v191, v123, v117
	v_cvt_pk_bf16_f32 v116, v120, v121
	v_cvt_pk_bf16_f32 v117, v122, v123
	v_cvt_pk_bf16_f32 v118, v124, v125
	v_cvt_pk_bf16_f32 v119, v126, v127
	s_waitcnt lgkmcnt(10)
	v_mfma_f32_32x32x16_bf16 v[80:95], v[140:143], v[144:147], v[80:95]
	v_add_f32_e32 v120, v124, v187
	v_add_f32_e32 v121, v125, v191
	v_add_f32_e32 v120, v126, v120
	v_add_f32_e32 v121, v127, v121
	v_permlane32_swap_b32_e32 v116, v118
	v_permlane32_swap_b32_e32 v117, v119
	ds_read_b64_tr_b16 v[220:221], v208 offset:0x1200
	ds_read_b64_tr_b16 v[222:223], v208 offset:0x1a00
	ds_read_b64_tr_b16 v[224:225], v208 offset:0x2200
	ds_read_b64_tr_b16 v[226:227], v208 offset:0x2a00
	s_waitcnt lgkmcnt(12)
	v_mfma_f32_32x32x16_bf16 v[48:63], v[128:131], v[200:203], v[48:63]
	v_max_f32_e32 v122, v97, v97
	v_max_f32_e32 v123, v96, v96
	v_max_f32_e32 v122, v123, v122
	v_max3_f32 v123, v99, v100, v101
	v_max3_f32 v122, v122, v98, v102
	v_max3_f32 v123, v123, v104, v105
	ds_read_b64_tr_b16 v[200:201], v208 offset:0x3200
	ds_read_b64_tr_b16 v[202:203], v208 offset:0x3a00
	s_waitcnt lgkmcnt(12)
	v_mfma_f32_32x32x16_bf16 v[48:63], v[132:135], v[192:195], v[48:63]
	v_max3_f32 v122, v122, v103, v106
	v_max3_f32 v123, v123, v108, v109
	v_max3_f32 v122, v122, v107, v110
	v_max3_f32 v122, v122, v111, v123
	v_add_f32_e32 v120, v120, v121
	v_mov_b32_e32 v121, v120
	ds_read_b64_tr_b16 v[192:193], v208 offset:0x400
	ds_read_b64_tr_b16 v[194:195], v208 offset:0xc00
	s_waitcnt lgkmcnt(12)
	v_mfma_f32_32x32x16_bf16 v[48:63], v[112:115], v[204:207], v[48:63]
	v_max3_f32 v123, v80, v81, v82
	v_max3_f32 v124, v83, v84, v85
	v_max3_f32 v123, v123, v86, v87
	v_max3_f32 v124, v124, v88, v89
	v_permlane32_swap_b32_e32 v120, v121
	v_max3_f32 v123, v123, v90, v91
	ds_read_b64_tr_b16 v[204:205], v208 offset:0x1400
	ds_read_b64_tr_b16 v[206:207], v208 offset:0x1c00
	s_waitcnt lgkmcnt(12)
	v_mfma_f32_32x32x16_bf16 v[48:63], v[116:119], v[212:215], v[48:63]
	v_max3_f32 v124, v124, v92, v93
	v_max3_f32 v123, v123, v94, v95
	v_max3_f32 v122, v122, v123, v124
	v_mov_b32_e32 v123, v122
	ds_read_b64_tr_b16 v[212:213], v208 offset:0x2400
	ds_read_b64_tr_b16 v[214:215], v208 offset:0x2c00
	s_waitcnt lgkmcnt(12)
	v_mfma_f32_32x32x16_bf16 v[32:47], v[128:131], v[216:219], v[32:47]
	v_permlane32_swap_b32_e32 v122, v123
	v_max_f32_e32 v123, v123, v123
	v_max_f32_e32 v122, v122, v122
	v_max_f32_e32 v122, v122, v123
	v_cmp_lt_f32_e32 vcc, s47, v122
	v_mov_b32_e32 v187, 1.0
	s_cbranch_vccnz .LBB0_733
.Lattn_m1_res2:
	ds_read_b64_tr_b16 v[216:217], v208 offset:0x3400
	ds_read_b64_tr_b16 v[218:219], v208 offset:0x3c00
	s_waitcnt lgkmcnt(12)
	v_mfma_f32_32x32x16_bf16 v[32:47], v[132:135], v[220:223], v[32:47]
	v_exp_f32_e32 v96, v96
	v_exp_f32_e32 v97, v97
	v_exp_f32_e32 v98, v98
	ds_read_b64_tr_b16 v[220:221], v208 offset:0x600
	ds_read_b64_tr_b16 v[222:223], v208 offset:0xe00
	s_waitcnt lgkmcnt(12)
	v_mfma_f32_32x32x16_bf16 v[32:47], v[112:115], v[224:227], v[32:47]
	v_exp_f32_e32 v99, v99
	v_exp_f32_e32 v100, v100
	v_exp_f32_e32 v101, v101
	ds_read_b64_tr_b16 v[224:225], v208 offset:0x1600
	ds_read_b64_tr_b16 v[226:227], v208 offset:0x1e00
	s_waitcnt lgkmcnt(12)
	v_mfma_f32_32x32x16_bf16 v[32:47], v[116:119], v[200:203], v[32:47]
	v_exp_f32_e32 v102, v102
	v_exp_f32_e32 v103, v103
	v_exp_f32_e32 v104, v104
	ds_read_b64_tr_b16 v[200:201], v208 offset:0x2600
	ds_read_b64_tr_b16 v[202:203], v208 offset:0x2e00
	s_waitcnt lgkmcnt(12)
	v_mfma_f32_32x32x16_bf16 v[16:31], v[128:131], v[192:195], v[16:31]
	v_exp_f32_e32 v105, v105
	v_exp_f32_e32 v106, v106
	v_exp_f32_e32 v107, v107
	ds_read_b64_tr_b16 v[192:193], v208 offset:0x3600
	ds_read_b64_tr_b16 v[194:195], v208 offset:0x3e00
	s_waitcnt lgkmcnt(12)
	v_mfma_f32_32x32x16_bf16 v[16:31], v[132:135], v[204:207], v[16:31]
	v_exp_f32_e32 v108, v108
	v_exp_f32_e32 v109, v109
	v_exp_f32_e32 v110, v110
	s_waitcnt lgkmcnt(10)
	v_mfma_f32_32x32x16_bf16 v[16:31], v[112:115], v[212:215], v[16:31]
	v_exp_f32_e32 v111, v111
	v_exp_f32_e32 v80, v80
	v_exp_f32_e32 v81, v81
	s_waitcnt lgkmcnt(8)
	v_mfma_f32_32x32x16_bf16 v[16:31], v[116:119], v[216:219], v[16:31]
	v_exp_f32_e32 v82, v82
	v_exp_f32_e32 v83, v83
	v_exp_f32_e32 v84, v84
	s_waitcnt lgkmcnt(6)
	v_mfma_f32_32x32x16_bf16 v[0:15], v[128:131], v[220:223], v[0:15]
	v_exp_f32_e32 v85, v85
	v_exp_f32_e32 v86, v86
	v_exp_f32_e32 v87, v87
	s_waitcnt lgkmcnt(4)
	v_mfma_f32_32x32x16_bf16 v[0:15], v[132:135], v[224:227], v[0:15]
	v_exp_f32_e32 v88, v88
	v_exp_f32_e32 v89, v89
	v_exp_f32_e32 v90, v90
	s_waitcnt lgkmcnt(2)
	v_mfma_f32_32x32x16_bf16 v[0:15], v[112:115], v[200:203], v[0:15]
	v_exp_f32_e32 v91, v91
	v_exp_f32_e32 v92, v92
	v_exp_f32_e32 v93, v93
	s_waitcnt lgkmcnt(0)
	v_mfma_f32_32x32x16_bf16 v[0:15], v[116:119], v[192:195], v[0:15]
	v_exp_f32_e32 v94, v94
	v_exp_f32_e32 v95, v95
	v_cmp_gt_f32_e32 vcc, 1.0, v187
	s_cbranch_vccz .LBB0_730
	s_and_saveexec_b64 s[52:53], s[0:1]
	ds_write_b32 v180, v187 offset:128
	s_or_b64 exec, exec, s[52:53]
	s_waitcnt lgkmcnt(0)
	v_add_u32_e32 v126, s19, v168
	ds_read_b128 v[112:115], v126 offset:224
	ds_read_b128 v[116:119], v126 offset:192
	ds_read_b128 v[122:125], v126 offset:160
	ds_read_b128 v[126:129], v126 offset:128
	s_waitcnt lgkmcnt(3)
	v_pk_mul_f32 v[60:61], v[60:61], v[112:113]
	s_waitcnt lgkmcnt(2)
	v_pk_mul_f32 v[56:57], v[56:57], v[116:117]
	s_waitcnt lgkmcnt(1)
	v_pk_mul_f32 v[52:53], v[52:53], v[122:123]
	v_pk_mul_f32 v[62:63], v[62:63], v[114:115]
	v_pk_mul_f32 v[58:59], v[58:59], v[118:119]
	v_pk_mul_f32 v[54:55], v[54:55], v[124:125]
	s_waitcnt lgkmcnt(0)
	v_pk_mul_f32 v[50:51], v[50:51], v[128:129]
	v_pk_mul_f32 v[48:49], v[48:49], v[126:127]
	v_pk_mul_f32 v[44:45], v[44:45], v[112:113]
	v_pk_mul_f32 v[40:41], v[40:41], v[116:117]
	v_pk_mul_f32 v[36:37], v[36:37], v[122:123]
	v_pk_mul_f32 v[46:47], v[46:47], v[114:115]
	v_pk_mul_f32 v[42:43], v[42:43], v[118:119]
	v_pk_mul_f32 v[38:39], v[38:39], v[124:125]
	v_pk_mul_f32 v[34:35], v[34:35], v[128:129]
	v_pk_mul_f32 v[32:33], v[32:33], v[126:127]
	v_pk_mul_f32 v[28:29], v[28:29], v[112:113]
	v_pk_mul_f32 v[24:25], v[24:25], v[116:117]
	v_pk_mul_f32 v[20:21], v[20:21], v[122:123]
	v_pk_mul_f32 v[30:31], v[30:31], v[114:115]
	v_pk_mul_f32 v[26:27], v[26:27], v[118:119]
	v_pk_mul_f32 v[22:23], v[22:23], v[124:125]
	v_pk_mul_f32 v[18:19], v[18:19], v[128:129]
	v_pk_mul_f32 v[16:17], v[16:17], v[126:127]
	v_pk_mul_f32 v[12:13], v[12:13], v[112:113]
	v_pk_mul_f32 v[8:9], v[8:9], v[116:117]
	v_pk_mul_f32 v[4:5], v[4:5], v[122:123]
	v_pk_mul_f32 v[14:15], v[14:15], v[114:115]
	v_pk_mul_f32 v[10:11], v[10:11], v[118:119]
	v_pk_mul_f32 v[6:7], v[6:7], v[124:125]
	v_pk_mul_f32 v[2:3], v[2:3], v[128:129]
	v_pk_mul_f32 v[0:1], v[0:1], v[126:127]
